# mixer B item prologue: sink-logit load no longer waited for before the q/k/v row loads are issued (one round trip less per item)
# speedup vs baseline: 1.0028x; 1.0028x over previous
; #define LAS __attribute__((address_space(3)))
; __device__ __forceinline__ const float* argp(const Frame& F, int idx) { unsigned long long p = F.kargs; asm volatile("" : "+s"(p)); return ((const float* const __attribute__((address_space(4)))*)p)[idx]; }
; __device__ __forceinline__ int v_rd_base(int lane) { return ((lane & 3) << 3) | (((lane >> 2) & 3) << 6) | (((lane >> 4) & 1) << 5) | (((lane >> 5) & 1) << 8); }
; #define WSLOAD(n) do { _Pragma("unroll") for (int i_ = 0; i_ < 4; ++i_) { int u_ = WUKB(n) + sr4 + 16 * i_; u_ = min(max(u_, 0), I.SU - 1); \
;       const bf16_t* rp_ = I.qkv + (size_t)(I.seq_base + clsw + I.dil * u_) * I.W + sc4; stv[i_] = LDG(bf16x8, rp_ + I.vcol); stk[i_] = LDG(bf16x8, rp_ + I.kcol); } } while (0)
; #define WSWRITE(b) do { _Pragma("unroll") for (int i_ = 0; i_ < 4; ++i_) { *(LAS bf16x8*)(Vh + (b) * SHM_V + v_st(sr4 + 16 * i_, sc4)) = stv[i_]; \
;       *(LAS bf16x8*)(Kh + (b) * SHM_K + KSWZ(sr4 + 16 * i_, sc4 * 2)) = stk[i_]; } } while (0)
; template <int WIN, bool ALIBI, int EPI, bool SINK>
; __device__ __forceinline__ void attn_item(const Item& I, char* lds, int tid_in) {
;     ...
;   const int hh = wid >> 2, tl = tid & 255, sr4 = tl >> 4, sc4 = (tl & 15) * 8;
;   LAS char* Vh = V_lds + hh * (2 * (SHM_V + SHM_K)); LAS char* Kh = Vh + 2 * SHM_V;
;   const int vbh = (int)(unsigned)(uintptr_t)Vh + v_rd_base(lane);
;   const int clsw = I.c0 + wcls, NTw = two ? 2 : (128 + 2 * WIN) / 64, ukbw = two ? 0 : I.u0 + 128 * hh - WIN;
;   bf16x8 stv[4], stk[4];
;     ...
;   WSLOAD(0); asm volatile("s_waitcnt vmcnt(0)" ::: "memory"); WSWRITE(0); if (1 < NTw) WSLOAD(1); __syncthreads();
; template <int MODE> __device__ __forceinline__ void phase_attn_fast(const Frame& F0) {
;     ...
;     } else { const int kvh = d.h >> 2; I.W = 3072; I.qcol = d.h * 128; I.kcol = 2048 + kvh * 128; I.vcol = 2560 + kvh * 128; I.ocol = d.h * 128;
;       const float slope2 = exp2f(-0.5f * (float)(d.h + 1)) * LOG2E;
;       if (MODE == 0) { I.ukb0 = 0; I.NT = d.S / 64; I.ropetab = (const float*)(F.ws + WS_ROPE); I.qgain = argp(F, 9); fa::attn_item<0, false, 0, false>(I, (char*)F.lds, F.tid); }
;       if (MODE == 1) { I.ukb0 = I.u0 - 128; I.NT = 8; I.nslope = -slope2; I.sink2 = argp(F, 13)[d.h] * LOG2E; fa::attn_item<128, true, 0, true>(I, (char*)F.lds, F.tid); }
.LBB0_937:
	s_lshr_b32 s13, s12, s13
	s_and_b32 s5, s5, s12
	s_lshl_b32 s31, s5, 8
	s_lshl_b32 s5, s13, 5
	s_and_b32 s26, s13, 15
	s_and_b32 s5, s5, 0x180
	s_or_b32 s27, s5, 0x800
	s_or_b32 s28, s5, 0xa00
	s_add_i32 s5, s26, 1
	v_cvt_f32_ubyte0_e32 v0, s5
	v_mul_f32_e32 v2, -0.5, v0
	s_mov_b32 s5, 0xc2fc0000
	s_lshl_b32 s12, s26, 7
	v_cmp_gt_f32_e32 vcc, s5, v2
	s_and_b64 s[24:25], vcc, exec
	s_mov_b64 s[24:25], s[40:41]
	v_cndmask_b32_e32 v2, 0, v230, vcc
	v_fmac_f32_e32 v2, -0.5, v0
	v_exp_f32_e32 v0, v2
	s_load_dwordx2 s[24:25], s[24:25], 0x68
	s_cselect_b32 s5, 0xffffffc0, 0
	v_ldexp_f32 v0, v0, s5
	s_lshl_b32 s5, s26, 2
	v_mul_f32_e32 v167, 0xbfb8aa3b, v0
	v_mov_b32_e32 v0, s5
	s_waitcnt lgkmcnt(0)
	global_load_dword v170, v0, s[24:25]
	v_mov_b32_e32 v15, v164
	v_mov_b64_e32 v[2:3], s[42:43]
	v_readfirstlane_b32 s5, v15
	s_ashr_i32 s24, s5, 6
	v_and_b32_e32 v168, 31, v15
	s_lshl_b32 s48, s24, 5
	v_bfe_u32 v169, v15, 5, 1
	s_lshl_b32 s72, s26, 8
	s_and_b32 s25, s5, 0x3fffffc0
	s_lshl_b32 s25, s25, 2
	s_ashr_i32 s5, s5, 8
	s_add_i32 s29, s25, 0
	v_lshlrev_b32_e32 v44, 3, v15
	s_lshl_b32 s25, s5, 16
	s_lshl_b32 s5, s5, 7
	v_and_b32_e32 v165, 63, v15
	v_lshlrev_b32_e32 v171, 2, v169
	v_lshlrev_b32_e32 v166, 4, v15
	s_add_i32 s30, s25, 0
	s_add_i32 s25, s31, s5
	v_bfe_u32 v17, v15, 4, 4
	s_add_i32 s5, s25, 0xffffff80
	v_or_b32_e32 v13, s5, v17
	s_add_i32 s26, s4, -1
	v_mov_b32_e32 v11, v1
	v_lshrrev_b32_e32 v18, 4, v15
	v_bfe_u32 v45, v15, 4, 2
	s_add_i32 s29, s29, 0x20000
	v_add_u32_e32 v189, 0x80, v13
	s_mov_b32 s13, 0
	v_lshl_add_u32 v180, v168, 8, s30
	v_lshl_add_u32 v177, v168, 2, s29
	v_mov_b32_e32 v190, 1.0
	s_lshl_b32 s46, s27, 1
	s_mov_b32 s51, 0
	v_or_b32_e32 v0, s48, v168
	v_add_u32_e32 v4, s31, v0
	v_add_u32_e32 v0, s9, v4
	v_mad_i64_i32 v[2:3], s[36:37], v0, s89, v[2:3]
	v_lshl_add_u64 v[2:3], v[2:3], 0, s[72:73]
	v_lshlrev_b32_e32 v0, 4, v169
	v_lshl_add_u64 v[2:3], v[2:3], 0, v[0:1]
	global_load_dwordx4 v[98:101], v[2:3], off
	global_load_dwordx4 v[102:105], v[2:3], off offset:32
	global_load_dwordx4 v[106:109], v[2:3], off offset:64
	global_load_dwordx4 v[110:113], v[2:3], off offset:96
	global_load_dwordx4 v[114:117], v[2:3], off offset:128
	global_load_dwordx4 v[118:121], v[2:3], off offset:160
	global_load_dwordx4 v[122:125], v[2:3], off offset:192
	global_load_dwordx4 v[126:129], v[2:3], off offset:224
	v_sub_u32_e32 v2, 0, v4
	v_max_i32_e32 v12, 0xffffff80, v2
	v_xad_u32 v2, v4, -1, s4
	v_min_i32_e32 v19, 0x80, v2
	v_and_b32_e32 v2, 0x78, v44
	v_sub_u32_e32 v16, v171, v4
	v_lshlrev_b32_e32 v10, 1, v2
	v_lshlrev_b32_e32 v2, 3, v165
	v_and_b32_e32 v3, 0xc0, v166
	v_lshlrev_b32_e32 v4, 1, v15
	v_and_or_b32 v3, v2, 24, v3
	v_and_b32_e32 v4, 32, v4
	v_and_b32_e32 v2, 0x100, v2
	v_or3_b32 v14, v3, v4, v2
	v_max_i32_e32 v2, 0, v13
	v_min_u32_e32 v2, s26, v2
	v_lshl_add_u64 v[162:163], s[42:43], 0, v[10:11]
	v_add_u32_e32 v2, s9, v2
	v_max_i32_e32 v11, -16, v13
	v_mad_i64_i32 v[6:7], s[4:5], v2, s89, v[162:163]
	s_lshl_b32 s72, s28, 1
	v_add_u32_e32 v11, 16, v11
	v_lshl_add_u64 v[2:3], v[6:7], 0, s[72:73]
	v_min_u32_e32 v11, s26, v11
	global_load_dwordx4 v[2:5], v[2:3], off
	v_add_u32_e32 v11, s9, v11
	v_mad_i64_i32 v[24:25], s[36:37], v11, s89, v[162:163]
	v_max_i32_e32 v11, 0xffffffe0, v13
	v_add_u32_e32 v11, 32, v11
	v_min_u32_e32 v11, s26, v11
	s_lshl_b32 s4, s27, 1
	s_mov_b32 s5, s73
	v_add_u32_e32 v11, s9, v11
	v_lshl_add_u64 v[6:7], v[6:7], 0, s[4:5]
	v_mad_i64_i32 v[32:33], s[36:37], v11, s89, v[162:163]
	v_max_i32_e32 v11, 0xffffffd0, v13
	global_load_dwordx4 v[6:9], v[6:7], off
	v_lshl_add_u64 v[20:21], v[24:25], 0, s[72:73]
	v_add_u32_e32 v11, 48, v11
	global_load_dwordx4 v[20:23], v[20:21], off
	v_lshl_add_u64 v[24:25], v[24:25], 0, s[4:5]
	v_min_u32_e32 v11, s26, v11
	global_load_dwordx4 v[24:27], v[24:25], off
	v_lshl_add_u64 v[28:29], v[32:33], 0, s[72:73]
	v_add_u32_e32 v11, s9, v11
	global_load_dwordx4 v[28:31], v[28:29], off
	v_lshl_add_u64 v[32:33], v[32:33], 0, s[4:5]
	v_mad_i64_i32 v[40:41], s[36:37], v11, s89, v[162:163]
	global_load_dwordx4 v[32:35], v[32:33], off
	v_lshl_add_u64 v[36:37], v[40:41], 0, s[72:73]
	global_load_dwordx4 v[36:39], v[36:37], off
	v_lshl_add_u64 v[40:41], v[40:41], 0, s[4:5]
	global_load_dwordx4 v[40:43], v[40:41], off
	v_bfe_u32 v11, v44, 5, 2
	v_lshrrev_b32_e32 v44, 5, v15
	v_and_or_b32 v44, v44, 4, v45
	v_and_or_b32 v11, v18, 4, v11
	v_cvt_f32_i32_e32 v172, v19
	v_and_b32_e32 v19, 48, v10
	v_lshl_add_u32 v44, v44, 6, s30
	v_lshlrev_b32_e32 v11, 9, v11
	s_add_i32 s48, s48, s31
	s_movk_i32 s31, 0x70
	v_add3_u32 v174, v44, v19, v11
	s_waitcnt vmcnt(0)
; #define LAS __attribute__((address_space(3)))
; __device__ __forceinline__ int v_rd_base(int lane) { return ((lane & 3) << 3) | (((lane >> 2) & 3) << 6) | (((lane >> 4) & 1) << 5) | (((lane >> 5) & 1) << 8); }
; #define WSLOAD(n) do { _Pragma("unroll") for (int i_ = 0; i_ < 4; ++i_) { int u_ = WUKB(n) + sr4 + 16 * i_; u_ = min(max(u_, 0), I.SU - 1); \
;       const bf16_t* rp_ = I.qkv + (size_t)(I.seq_base + clsw + I.dil * u_) * I.W + sc4; stv[i_] = LDG(bf16x8, rp_ + I.vcol); stk[i_] = LDG(bf16x8, rp_ + I.kcol); } } while (0)
; #define WSWRITE(b) do { _Pragma("unroll") for (int i_ = 0; i_ < 4; ++i_) { *(LAS bf16x8*)(Vh + (b) * SHM_V + v_st(sr4 + 16 * i_, sc4)) = stv[i_]; \
;       *(LAS bf16x8*)(Kh + (b) * SHM_K + KSWZ(sr4 + 16 * i_, sc4 * 2)) = stk[i_]; } } while (0)
; template <int WIN, bool ALIBI, int EPI, bool SINK>
; __device__ __forceinline__ void attn_item(const Item& I, char* lds, int tid_in) {
;     ...
;   const int hh = wid >> 2, tl = tid & 255, sr4 = tl >> 4, sc4 = (tl & 15) * 8;
;   LAS char* Vh = V_lds + hh * (2 * (SHM_V + SHM_K)); LAS char* Kh = Vh + 2 * SHM_V;
;   const int vbh = (int)(unsigned)(uintptr_t)Vh + v_rd_base(lane);
;   const int clsw = I.c0 + wcls, NTw = two ? 2 : (128 + 2 * WIN) / 64, ukbw = two ? 0 : I.u0 + 128 * hh - WIN;
;   bf16x8 stv[4], stk[4];
;     ...
;   WSLOAD(0); asm volatile("s_waitcnt vmcnt(0)" ::: "memory"); WSWRITE(0); if (1 < NTw) WSLOAD(1); __syncthreads();
;   for (int n = 0; n < NTw; ++n) { const int bsel = n & 1;
	v_mul_f32_e32 v170, 0x3fb8aa3b, v170
	v_bitop3_b32 v10, v10, v15, s31 bitop3:0x78
	v_cvt_f32_i32_e32 v176, v16
	v_cvt_f32_i32_e32 v178, v12
	v_add_u32_e32 v179, s30, v14
	v_mov_b32_e32 v14, v1
	v_mov_b32_e32 v15, v1
	v_bitop3_b32 v181, v0, v166, s31 bitop3:0x78
	v_add_u32_e32 v173, s29, v0
	v_mov_b32_e32 v11, v1
	v_mov_b32_e32 v12, v1
	s_add_i32 s49, s48, 0xffffff80
	s_add_i32 s50, s48, 0x9f
	ds_write_b128 v174, v[2:5]
	v_lshlrev_b32_e32 v2, 8, v17
	v_add3_u32 v175, s30, v10, v2
	v_or_b32_e32 v2, 64, v13
	v_max_i32_e32 v2, 0, v2
	v_min_u32_e32 v2, s26, v2
	v_add_u32_e32 v2, s9, v2
	v_mad_i64_i32 v[2:3], s[36:37], v2, s89, v[162:163]
	ds_write_b128 v175, v[6:9] offset:32768
	ds_write_b128 v174, v[20:23] offset:4096
	ds_write_b128 v175, v[24:27] offset:36864
	ds_write_b128 v174, v[28:31] offset:8192
	ds_write_b128 v175, v[32:35] offset:40960
	ds_write_b128 v174, v[36:39] offset:12288
	ds_write_b128 v175, v[40:43] offset:45056
	v_lshl_add_u64 v[4:5], v[2:3], 0, s[72:73]
	v_lshl_add_u64 v[2:3], v[2:3], 0, s[4:5]
	global_load_dwordx4 v[130:133], v[4:5], off
	global_load_dwordx4 v[134:137], v[2:3], off
	v_or_b32_e32 v2, 0x50, v13
	v_max_i32_e32 v2, 0, v2
	v_min_u32_e32 v2, s26, v2
	v_add_u32_e32 v2, s9, v2
	v_mad_i64_i32 v[2:3], s[36:37], v2, s89, v[162:163]
	v_lshl_add_u64 v[4:5], v[2:3], 0, s[72:73]
	v_lshl_add_u64 v[2:3], v[2:3], 0, s[4:5]
	global_load_dwordx4 v[138:141], v[4:5], off
	global_load_dwordx4 v[142:145], v[2:3], off
	v_or_b32_e32 v2, 0x60, v13
	v_max_i32_e32 v2, 0, v2
	v_min_u32_e32 v2, s26, v2
	v_add_u32_e32 v2, s9, v2
	v_mad_i64_i32 v[2:3], s[36:37], v2, s89, v[162:163]
	v_lshl_add_u64 v[4:5], v[2:3], 0, s[72:73]
	v_lshl_add_u64 v[2:3], v[2:3], 0, s[4:5]
	global_load_dwordx4 v[146:149], v[4:5], off
	global_load_dwordx4 v[150:153], v[2:3], off
	v_or_b32_e32 v2, 0x70, v13
	v_max_i32_e32 v2, 0, v2
	v_min_u32_e32 v2, s26, v2
	v_add_u32_e32 v2, s9, v2
	v_mad_i64_i32 v[2:3], s[36:37], v2, s89, v[162:163]
	v_lshl_add_u64 v[4:5], v[2:3], 0, s[72:73]
	v_lshl_add_u64 v[2:3], v[2:3], 0, s[4:5]
	global_load_dwordx4 v[154:157], v[4:5], off
	global_load_dwordx4 v[158:161], v[2:3], off
	v_and_b32_e32 v2, 0x70, v166
	s_movk_i32 s4, 0xe0
	v_bitop3_b32 v182, v0, v2, 32 bitop3:0x36
	v_bitop3_b32 v183, v0, v2, 64 bitop3:0x36
	v_bitop3_b32 v184, v0, v2, s93 bitop3:0x36
	v_bitop3_b32 v185, v0, v2, s85 bitop3:0x36
	v_bitop3_b32 v186, v0, v2, s67 bitop3:0x36
	v_bitop3_b32 v187, v0, v2, s83 bitop3:0x36
	v_bitop3_b32 v188, v0, v2, s4 bitop3:0x36
	v_mov_b32_e32 v0, v1
	v_mov_b32_e32 v2, v1
	v_mov_b32_e32 v3, v1
	v_mov_b32_e32 v4, v1
	v_mov_b32_e32 v5, v1
	v_mov_b32_e32 v6, v1
	v_mov_b32_e32 v7, v1
	v_mov_b32_e32 v8, v1
	v_mov_b32_e32 v9, v1
	v_mov_b32_e32 v10, v1
	v_mov_b32_e32 v13, v1
	v_mov_b64_e32 v[64:65], v[14:15]
	v_mov_b64_e32 v[48:49], v[14:15]
	v_mov_b64_e32 v[32:33], v[14:15]
	v_mov_b64_e32 v[62:63], v[12:13]
	v_mov_b64_e32 v[60:61], v[10:11]
	v_mov_b64_e32 v[58:59], v[8:9]
	v_mov_b64_e32 v[56:57], v[6:7]
	v_mov_b64_e32 v[54:55], v[4:5]
	v_mov_b64_e32 v[52:53], v[2:3]
	v_mov_b64_e32 v[50:51], v[0:1]
	v_mov_b64_e32 v[46:47], v[12:13]
	v_mov_b64_e32 v[44:45], v[10:11]
	v_mov_b64_e32 v[42:43], v[8:9]
	v_mov_b64_e32 v[40:41], v[6:7]
	v_mov_b64_e32 v[38:39], v[4:5]
	v_mov_b64_e32 v[36:37], v[2:3]
	v_mov_b64_e32 v[34:35], v[0:1]
	v_mov_b64_e32 v[30:31], v[12:13]
	v_mov_b64_e32 v[28:29], v[10:11]
	v_mov_b64_e32 v[26:27], v[8:9]
	v_mov_b64_e32 v[24:25], v[6:7]
	v_mov_b64_e32 v[22:23], v[4:5]
	v_mov_b64_e32 v[20:21], v[2:3]
	v_mov_b64_e32 v[18:19], v[0:1]
	v_mov_b64_e32 v[16:17], v[14:15]
	v_cmp_gt_u32_e64 s[36:37], 32, v165
	s_lshl_b32 s72, s28, 1
	v_mov_b64_e32 v[14:15], v[12:13]
	v_mov_b64_e32 v[12:13], v[10:11]
	v_mov_b64_e32 v[10:11], v[8:9]
	v_mov_b64_e32 v[8:9], v[6:7]
	v_mov_b64_e32 v[6:7], v[4:5]
	v_mov_b64_e32 v[4:5], v[2:3]
	v_mov_b64_e32 v[2:3], v[0:1]
	s_waitcnt lgkmcnt(0)
	s_barrier
	s_branch .LBB0_939
